# v27 + sg items remapped so the four channel groups of one token chunk (same v rows) run on one XCC
# baseline (speedup 1.0000x reference)
; __device__ __forceinline__ int bid_s() { int b = blockIdx.x; asm volatile("" : "+s"(b)); return b; }
; __device__ __forceinline__ void phase2(int l, int s, unsigned char* shm) {
;     ...
;     for (int it = bid_s(); it < 512; it += gridDim.x) sg_item(B, l, s, it, shm);
.LBB0_544:
	s_add_u32 s40, s44, 0x19c00000
	s_addc_u32 s41, s45, 0
	s_and_b32 s27, s87, 0xffffffe0
	s_and_b32 s2, s87, 7
	s_lshl_b32 s2, s2, 2
	s_or_b32 s27, s27, s2
	s_bfe_u32 s2, s87, 0x20003
	s_or_b32 s27, s27, s2
	s_cmpk_gt_i32 s27, 0x1ff
	s_cbranch_scc1 .LBB0_554
	s_add_u32 s16, s44, 0xcc00000
	s_addc_u32 s17, s45, 0
	s_lshl_b32 s30, s69, 9
	s_lshl_b32 s29, s69, 2
	s_lshl_b64 s[18:19], s[30:31], 2
	s_branch .LBB0_547
